# static s_setprio 1 for waves 4-7 during the attention phase (plus DPP shuffles)
# speedup vs baseline: 1.0121x; 1.0059x over previous
; #define LAS __attribute__((address_space(3)))
; __device__ __forceinline__ void attn_fast(const Ptrs& P, LAS unsigned char* lds, int G, int bid) {
;     const int tid = threadIdx.x, lane = tid & 63, w = __builtin_amdgcn_readfirstlane(tid >> 6), fr = lane & 15, fq = lane >> 4, qi = fr >> 2, hh = fr & 3;
;     LAS float* IMP = (LAS float*)(lds + 98304) + w * (8 * 132);
;     LAS unsigned* SELM = (LAS unsigned*)(lds + 132096);
;     const h16* U = (const h16*)(P.ws + WS_U); h16* Y = (h16*)(P.ws + WS_YACC);
;     const float SC = 0.08838834764831845f * 1.4426950408889634f;
;     const int NEGBIG = -(1 << 30);
;     unsigned kl[4]; kl[0] = (unsigned)lane; kl[1] = kl[2] = kl[3] = 0u;
;     const int vz = (4 * fq + (fr >> 2)) & 7;
;     const unsigned vl0 = (unsigned)((4 * fq + (fr >> 2)) * 256 + 8 * (fr & 1) + 16 * ((fr >> 1) & 1));
;     const int nunits = (512 + G - 1) / G;
.LBB0_501:
.LBB0_502:
	s_cmp_lt_i32 s26, 6
	s_cselect_b64 s[0:1], -1, 0
	s_cmp_gt_i32 s27, 5
	s_cselect_b64 s[4:5], -1, 0
	s_and_b64 s[0:1], s[0:1], s[4:5]
	s_andn2_b64 vcc, exec, s[0:1]
	s_cbranch_vccnz .LBB0_694
	s_abs_i32 s1, s95
	v_cvt_f32_u32_e32 v2, s1
	s_sub_i32 s5, 0, s1
	s_add_i32 s3, s95, 0x1ff
	s_xor_b32 s4, s3, s95
	v_rcp_iflag_f32_e32 v2, v2
	s_abs_i32 s3, s3
	s_ashr_i32 s4, s4, 31
	v_readfirstlane_b32 s0, v1
	v_mul_f32_e32 v2, 0x4f7ffffe, v2
	v_cvt_u32_f32_e32 v2, v2
	v_writelane_b32 v243, s68, 0
	s_mov_b32 s65, 0
	v_readfirstlane_b32 s6, v2
	s_mul_i32 s5, s5, s6
	s_mul_hi_u32 s5, s6, s5
	s_add_i32 s6, s6, s5
	s_mul_hi_u32 s5, s3, s6
	s_mul_i32 s6, s5, s1
	s_sub_i32 s3, s3, s6
	s_add_i32 s7, s5, 1
	s_sub_i32 s6, s3, s1
	s_cmp_ge_u32 s3, s1
	s_cselect_b32 s5, s7, s5
	s_cselect_b32 s3, s6, s3
	s_add_i32 s6, s5, 1
	s_cmp_ge_u32 s3, s1
	s_cselect_b32 s1, s6, s5
	v_writelane_b32 v243, s69, 1
	s_xor_b32 s1, s1, s4
	v_writelane_b32 v243, s78, 2
	s_sub_i32 s12, s1, s4
	s_cmp_lt_i32 s12, 1
	v_writelane_b32 v243, s79, 3
	v_writelane_b32 v243, s76, 4
	s_cbranch_scc1 .LBB0_630
	s_lshr_b32 s0, s0, 6
	s_cmp_lt_u32 s0, 4
	s_cbranch_scc1 .Lprio_skip
	s_setprio 1
.Lprio_skip:
	s_mul_i32 s1, s0, 0x1080
	s_add_i32 s85, s1, 0
	s_add_i32 s66, s85, 0x18000
	s_add_u32 s18, s24, 0xe564000
	s_addc_u32 s19, s25, 0
	s_add_u32 s20, s24, 0x25564000
	s_addc_u32 s21, s25, 0
	s_cmpk_lg_i32 s95, 0x100
	s_cselect_b64 s[14:15], -1, 0
	s_lshl_b32 s3, s2, 5
	s_and_b32 s3, s3, 32
	s_ashr_i32 s4, s2, 3
	s_add_i32 s3, s3, s4
	s_bfe_u32 s4, s2, 0x20001
	v_writelane_b32 v243, s4, 5
	v_bfe_u32 v4, v1, 4, 2
	v_writelane_b32 v243, s3, 6
	s_sub_i32 s3, 0x7f, s3
	s_lshl_b32 s70, s0, 3
	v_bfe_u32 v5, v1, 2, 2
	v_lshlrev_b32_e32 v173, 2, v4
	v_lshlrev_b32_e32 v2, 3, v1
	s_add_u32 s71, s24, 0x6364000
	v_or_b32_e32 v6, v173, v5
	v_and_b32_e32 v7, 24, v2
	v_and_b32_e32 v8, 3, v1
	s_addc_u32 s72, s25, 0
	v_lshl_or_b32 v174, v6, 8, v7
	v_writelane_b32 v243, s3, 7
	v_lshlrev_b32_e32 v9, 7, v8
	s_add_u32 s73, s24, 0x6464000
	v_cmp_eq_u32_e64 s[10:11], 0, v8
	v_lshlrev_b32_e32 v6, 5, v6
	v_mov_b32_e32 v8, 0xe0
	s_movk_i32 s3, 0x60
	s_addc_u32 s74, s25, 0
	s_lshl_b32 s75, s0, 11
	s_movk_i32 s0, 0xe0
	v_bitop3_b32 v180, v6, s3, v8 bitop3:0x6c
	s_movk_i32 s77, 0x80
	s_movk_i32 s3, 0xa0
	s_movk_i32 s78, 0xc0
	v_and_b32_e32 v177, 0xe0, v6
	v_bitop3_b32 v178, v6, 32, v8 bitop3:0x6c
	v_bitop3_b32 v179, v6, 64, v8 bitop3:0x6c
	v_bitop3_b32 v181, v6, s77, v8 bitop3:0x6c
	v_bitop3_b32 v182, v6, s3, v8 bitop3:0x6c
	v_bitop3_b32 v183, v6, s78, v8 bitop3:0x6c
	v_bitop3_b32 v184, v6, s0, v6 bitop3:0xc
	s_movk_i32 s3, 0x210
	v_mov_b32_e32 v6, s1
	v_mad_u32_u24 v6, v5, s3, v6
	v_or_b32_e32 v189, v6, v173
	v_add_u32_e32 v6, 0, v184
	v_lshlrev_b32_e32 v8, 10, v4
	s_movk_i32 s1, 0x4000
	v_add3_u32 v190, v6, v8, s1
	v_add_u32_e32 v6, 0, v183
	v_add3_u32 v192, v6, v8, s1
	v_add_u32_e32 v6, 0, v182
	v_add3_u32 v193, v6, v8, s1
	v_add_u32_e32 v6, 0, v181
	v_add3_u32 v194, v6, v8, s1
	v_add_u32_e32 v6, 0, v180
	v_add3_u32 v195, v6, v8, s1
	v_add_u32_e32 v6, 0, v179
	v_writelane_b32 v243, s96, 8
	v_or_b32_e32 v175, s70, v5
	v_lshlrev_b32_e32 v2, 3, v4
	v_lshlrev_b32_e32 v176, 6, v4
	v_lshl_or_b32 v191, v5, 8, v7
	v_add3_u32 v196, v6, v8, s1
	v_add_u32_e32 v6, 0, v178
	v_lshlrev_b32_e32 v4, 7, v4
	v_lshlrev_b32_e32 v5, 5, v5
	v_writelane_b32 v243, s97, 9
	v_and_b32_e32 v172, 63, v1
	s_add_i32 s76, s75, 0
	v_add3_u32 v197, v6, v8, s1
	v_add_u32_e32 v6, 0, v8
	v_bitop3_b32 v4, v4, s0, v5 bitop3:0xc8
	v_mbcnt_lo_u32_b32 v203, -1, 0
	v_writelane_b32 v243, s12, 10
	v_mov_b32_e32 v3, 0
	v_cmp_eq_u32_e64 s[4:5], 0, v172
	v_or_b32_e32 v185, 64, v172
	s_or_b32 s79, s75, 0x400
	v_lshlrev_b32_e32 v186, 4, v175
	v_or_b32_e32 v187, 0xffffffc0, v172
	v_lshl_add_u32 v188, v172, 2, s66
	s_add_i32 s80, s70, 0x80
	s_add_i32 s81, s75, 0x14400
	s_add_i32 s82, s75, 0x10400
	s_add_i32 s83, s75, 0x14000
	s_add_i32 s84, s75, 0x10000
	v_add3_u32 v198, v6, v4, s1
	s_add_i32 s85, s85, 0x18210
	s_movk_i32 s86, 0x2e00
	v_lshlrev_b32_e32 v166, 1, v2
	v_lshlrev_b32_e32 v199, 1, v9
	s_mov_b64 s[30:31], 0x4000
	s_add_i32 s87, s76, 0x8000
	s_mov_b64 s[34:35], 0x4400
	s_add_i32 s88, s76, 0x8400
	s_mov_b32 s89, 0x3e0293ee
	s_add_i32 s90, s76, 0x4400
	s_add_i32 s91, s76, 0xc000
	s_add_i32 s92, s76, 0xc400
	s_movk_i32 s93, 0x2000
	v_mov_b32_e32 v200, 0x3b8637bd
	v_mov_b32_e32 v201, 0x461c4000
	v_mov_b32_e32 v202, 0xff61b1e6
	v_mbcnt_hi_u32_b32 v204, -1, v203
	v_mov_b32_e32 v205, 0x2e00
	v_mov_b32_e32 v206, 0xf149f2ca
	v_writelane_b32 v243, s14, 11
	s_nop 1
	v_writelane_b32 v243, s15, 12
	v_lshrrev_b32_e32 v4, 4, v172
	v_add_u32_e32 v4, s70, v4
	v_and_b32_e32 v5, 15, v172
	v_mul_u32_u24_e32 v6, 0x2e00, v4
	v_xor_b32_e32 v7, v4, v5
	v_and_b32_e32 v7, 15, v7
	v_lshl_add_u32 v244, v7, 4, v6
	v_lshlrev_b32_e32 v7, 1, v4
	v_and_b32_e32 v7, 14, v7
	v_xor_b32_e32 v7, v7, v5
	v_lshl_add_u32 v245, v7, 4, v6
	v_add_u32_e32 v245, 0x200, v245
	v_add_u32_e32 v4, 4, v4
	v_add_u32_e32 v6, 0xb800, v6
	v_xor_b32_e32 v7, v4, v5
	v_and_b32_e32 v7, 15, v7
	v_lshl_add_u32 v246, v7, 4, v6
	v_lshlrev_b32_e32 v7, 1, v4
	v_and_b32_e32 v7, 14, v7
	v_xor_b32_e32 v7, v7, v5
	v_lshl_add_u32 v247, v7, 4, v6
	v_add_u32_e32 v247, 0x200, v247
	v_lshrrev_b32_e32 v4, 4, v172
	v_add_u32_e32 v4, s70, v4
	v_lshlrev_b32_e32 v6, 8, v4
	v_xor_b32_e32 v7, v4, v5
	v_and_b32_e32 v7, 15, v7
	v_lshl_add_u32 v250, v7, 4, v6
	v_lshlrev_b32_e32 v7, 1, v4
	v_and_b32_e32 v7, 14, v7
	v_xor_b32_e32 v7, v7, v5
	v_lshl_add_u32 v251, v7, 4, v6
	v_add_u32_e32 v4, 4, v4
	v_add_u32_e32 v6, 0x400, v6
	v_xor_b32_e32 v7, v4, v5
	v_and_b32_e32 v7, 15, v7
	v_lshl_add_u32 v252, v7, 4, v6
	v_lshlrev_b32_e32 v7, 1, v4
	v_and_b32_e32 v7, 14, v7
	v_xor_b32_e32 v7, v7, v5
	v_lshl_add_u32 v253, v7, 4, v6
	s_branch .LBB0_506

; #define PHASE_BEGIN(n) if (lo <= (n) && (n) < hi) {
; #define PHASE_END(n) if ((n) + 1 < hi) { if (G != 256) cg::this_grid().sync(); else xcd_barrier(xbar); } }
; __global__ void __launch_bounds__(NTHR, 2) mega(Args args) {
;     ...
;     PHASE_BEGIN(0) p0_prologue(P, lds, G, bid); PHASE_END(0)
;     PHASE_BEGIN(1) norm_mod_rows<false, false>(P.in[0], P.in[4], mod, 0, 2048, (h16*)(ws + WS_H), G, bid); PHASE_END(1)
;     PHASE_BEGIN(2) { pg8::Gemm g{(const h16*)(ws + WS_H), (const h16*)(ws + WS_WIN), NT, DINP, DM}; pg8::StaticOrder S; S.init(NT, DINP, G, bid);
;                   pg8::EpiF16<0> E{(h16*)(ws + WS_U), DINP}; pg8::gemm_phase<false>(lds, g, S, E); } PHASE_END(2)
;     PHASE_BEGIN(3) post_u_rows(P, G, bid); PHASE_END(3)
;     PHASE_BEGIN(4) compress_phase(P, lds, G, bid); PHASE_END(4)
;     PHASE_BEGIN(5) attn_fast(P, lds, G, bid); PHASE_END(5)
.LBB0_630:
	s_setprio 0
	v_readlane_b32 s78, v243, 2
	v_readlane_b32 s68, v243, 0
	s_cmp_lt_i32 s27, 7
	v_readlane_b32 s76, v243, 4
	v_readlane_b32 s79, v243, 3
	v_readlane_b32 s69, v243, 1
	s_cbranch_scc1 .LBB0_694
	s_waitcnt lgkmcnt(0)
	s_cmpk_eq_i32 s95, 0x100
	s_mov_b64 s[4:5], -1
	s_cbranch_scc1 .LBB0_643
	v_lshrrev_b32_e32 v2, 20, v0
	v_lshrrev_b32_e32 v3, 10, v0
	v_or_b32_e32 v2, v3, v2
	s_movk_i32 s0, 0x3ff
	v_and_or_b32 v2, v2, s0, v1
	v_cmp_eq_u32_e32 vcc, 0, v2
	s_waitcnt vmcnt(0)
	s_barrier
	s_and_saveexec_b64 s[4:5], vcc
	s_cbranch_execz .LBB0_642
	buffer_wbl2 sc1
	s_load_dwordx2 s[6:7], s[78:79], 0x58
	v_mov_b32_e32 v4, 0
	s_mov_b64 s[8:9], exec
	v_mbcnt_lo_u32_b32 v3, s8, 0
	v_mbcnt_hi_u32_b32 v3, s9, v3
	s_waitcnt lgkmcnt(0)
	global_load_dword v2, v4, s[6:7] offset:40
	v_cmp_eq_u32_e32 vcc, 0, v3
	s_and_saveexec_b64 s[10:11], vcc
	s_cbranch_execz .LBB0_635
	s_bcnt1_i32_b64 s0, s[8:9]
	v_mov_b32_e32 v5, s0
	global_atomic_add v5, v4, v5, s[6:7] offset:32 sc0
